# thr tile loop: 13 of 18 q_idx operand fragments kept in registers for the whole pass instead of re-read from LDS per key tile
# speedup vs baseline: 1.0031x; 1.0031x over previous
; DI void dsa_thr_item(const Params& p, int b, int qblk, char* smem) {
;     ...
;     for (int i = tid; i < 8192; i += 512) hist[i] = 0u;
;     __syncthreads();
;     const int shift = 24 - 8 * pass;
;     const unsigned mypref = pref[lr];
;     const u16* kib = (const u16*)(p.ws + OFF_KIF) + (size_t)b * 128 * 1024 + lane * 8;
;     bf16x8 kn0, kn1;
;     {
;       const int kt0 = min(wave, qblk);
;       kn0 = ldg8(kib + (size_t)kt0 * 1024); kn1 = ldg8(kib + (size_t)kt0 * 1024 + 512);
;     }
.LBB0_264:
	v_add_u32_e32 v1, 0x200, v1
	s_movk_i32 s0, 0x1dff
	v_cmp_lt_u32_e64 s[0:1], s0, v1
	ds_write_b32 v0, v53
	s_or_b64 s[52:53], s[0:1], s[52:53]
	v_add_u32_e32 v0, 0x800, v0
	s_andn2_b64 exec, exec, s[52:53]
	s_cbranch_execnz .LBB0_264
	s_or_b64 exec, exec, s[52:53]
	s_waitcnt lgkmcnt(0)
	s_barrier
	s_and_saveexec_b64 s[54:55], vcc
	s_cbranch_execz .LBB0_334
	global_load_dwordx4 v[36:39], v[56:57], off offset:1024
	global_load_dwordx4 v[32:35], v[56:57], off
	ds_read_b32 v94, v58 offset:32768
	ds_read_b128 v[184:187], v216 offset:33792
	ds_read_b128 v[188:191], v216 offset:33824
	ds_read_b128 v[192:195], v216 offset:33280
	ds_read_b128 v[196:199], v216 offset:33312
	ds_read_b128 v[200:203], v216 offset:33344
	ds_read_b128 v[220:223], v216 offset:33376
	ds_read_b128 v[224:227], v216 offset:33408
	ds_read_b128 v[228:231], v216 offset:33440
	ds_read_b128 v[232:235], v216 offset:33472
	ds_read_b128 v[236:239], v216 offset:33504
	ds_read_b128 v[240:243], v216 offset:33536
	ds_read_b128 v[244:247], v216 offset:33568
	ds_read_b128 v[248:251], v216 offset:33600
	s_waitcnt lgkmcnt(0)
	s_lshl_b32 s0, s72, 3
	s_sub_i32 s58, 24, s0
	s_mov_b64 s[60:61], 0
	v_mov_b32_e32 v96, v167
	s_branch .LBB0_268

; #define MFMA(a, b, c) __builtin_amdgcn_mfma_f32_32x32x16_bf16((a), (b), (c), 0, 0, 0)
; DI f32x16 zero16() { f32x16 z; for (int i = 0; i < 16; ++i) z[i] = 0.f; return z; }
; DI void dsa_thr_item(const Params& p, int b, int qblk, char* smem) {
;     ...
;     for (int kt = wave; kt <= qblk; kt += 8) {
;       const bf16x8 k0 = kn0, k1 = kn1;
;       {
;         const int ktn = min(kt + 8, qblk);
;         kn0 = ldg8(kib + (size_t)ktn * 1024); kn1 = ldg8(kib + (size_t)ktn * 1024 + 512);
;       }
;       float sc[16];
;       {
;         f32x16 a = zero16();
;         a = MFMA(k0, *reinterpret_cast<const bf16x8*>(qil + 256), a);
;         a = MFMA(k1, *reinterpret_cast<const bf16x8*>(qil + 256 + 16), a);
; #pragma unroll
;         for (int i = 0; i < 16; ++i) sc[i] = a[i];
;       }
; #pragma unroll
;       for (int hd = 0; hd < 8; ++hd) {
;         f32x16 a = zero16();
;         a = MFMA(k0, *reinterpret_cast<const bf16x8*>(qil + hd * 32), a);
;         a = MFMA(k1, *reinterpret_cast<const bf16x8*>(qil + hd * 32 + 16), a);
;         const float wh = wq[hd];
; #pragma unroll
;         for (int i = 0; i < 16; ++i) sc[i] = fmaf(fabsf(a[i]), wh, sc[i]);
;       }
.LBB0_268:
	v_mov_b32_e32 v97, v96
	v_add_u32_e32 v96, 8, v97
	v_min_i32_e32 v52, s71, v96
	v_lshlrev_b64 v[0:1], 11, v[52:53]
	s_waitcnt vmcnt(0)
	v_mov_b64_e32 v[42:43], v[38:39]
	s_waitcnt vmcnt(0)
	v_mov_b64_e32 v[46:47], v[34:35]
	v_lshl_add_u64 v[0:1], v[54:55], 0, v[0:1]
	v_mov_b64_e32 v[40:41], v[36:37]
	v_mov_b64_e32 v[44:45], v[32:33]
	global_load_dwordx4 v[32:35], v[0:1], off
	global_load_dwordx4 v[36:39], v[0:1], off offset:1024
	v_mfma_f32_32x32x16_bf16 v[104:119], v[44:47], v[184:187], 0
	v_mfma_f32_32x32x16_bf16 v[104:119], v[40:43], v[188:191], v[104:119]
	v_cmp_ne_u32_e64 s[0:1], s71, v97
	s_mov_b64 s[62:63], 0
	v_mfma_f32_32x32x16_bf16 v[120:135], v[44:47], v[192:195], 0
	v_mfma_f32_32x32x16_bf16 v[120:135], v[40:43], v[196:199], v[120:135]
	v_mfma_f32_32x32x16_bf16 v[136:151], v[44:47], v[200:203], 0
	v_mfma_f32_32x32x16_bf16 v[136:151], v[40:43], v[220:223], v[136:151]
	s_nop 9
	v_fma_f32 v152, |v120|, v79, v104
	v_fma_f32 v153, |v121|, v79, v105
	v_fma_f32 v154, |v122|, v79, v106
	v_fma_f32 v155, |v123|, v79, v107
	v_fma_f32 v156, |v124|, v79, v108
	v_fma_f32 v157, |v125|, v79, v109
	v_fma_f32 v158, |v126|, v79, v110
	v_fma_f32 v159, |v127|, v79, v111
	v_fma_f32 v160, |v128|, v79, v112
	v_fma_f32 v161, |v129|, v79, v113
	v_fma_f32 v98, |v130|, v79, v114
	v_fma_f32 v99, |v131|, v79, v115
	v_fma_f32 v100, |v132|, v79, v116
	v_fma_f32 v101, |v133|, v79, v117
	v_fma_f32 v102, |v134|, v79, v118
	v_fma_f32 v103, |v135|, v79, v119
	v_mfma_f32_32x32x16_bf16 v[104:119], v[44:47], v[224:227], 0
	v_mfma_f32_32x32x16_bf16 v[104:119], v[40:43], v[228:231], v[104:119]
	v_fma_f32 v152, |v136|, v80, v152
	v_fma_f32 v153, |v137|, v80, v153
	v_fma_f32 v154, |v138|, v80, v154
	v_fma_f32 v155, |v139|, v80, v155
	v_fma_f32 v156, |v140|, v80, v156
	v_fma_f32 v157, |v141|, v80, v157
	v_fma_f32 v158, |v142|, v80, v158
	v_fma_f32 v159, |v143|, v80, v159
	v_fma_f32 v160, |v144|, v80, v160
	v_fma_f32 v161, |v145|, v80, v161
	v_fma_f32 v98, |v146|, v80, v98
	v_fma_f32 v99, |v147|, v80, v99
	v_fma_f32 v100, |v148|, v80, v100
	v_fma_f32 v101, |v149|, v80, v101
	v_fma_f32 v102, |v150|, v80, v102
	v_fma_f32 v103, |v151|, v80, v103
	v_mfma_f32_32x32x16_bf16 v[120:135], v[44:47], v[232:235], 0
	v_mfma_f32_32x32x16_bf16 v[120:135], v[40:43], v[236:239], v[120:135]
	v_fma_f32 v152, |v104|, v81, v152
	v_fma_f32 v153, |v105|, v81, v153
	v_fma_f32 v154, |v106|, v81, v154
	v_fma_f32 v155, |v107|, v81, v155
	v_fma_f32 v156, |v108|, v81, v156
	v_fma_f32 v157, |v109|, v81, v157
	v_fma_f32 v158, |v110|, v81, v158
	v_fma_f32 v159, |v111|, v81, v159
	v_fma_f32 v160, |v112|, v81, v160
	v_fma_f32 v161, |v113|, v81, v161
	v_fma_f32 v98, |v114|, v81, v98
	v_fma_f32 v99, |v115|, v81, v99
	v_fma_f32 v100, |v116|, v81, v100
	v_fma_f32 v101, |v117|, v81, v101
	v_fma_f32 v102, |v118|, v81, v102
	v_fma_f32 v103, |v119|, v81, v103
	v_mfma_f32_32x32x16_bf16 v[136:151], v[44:47], v[240:243], 0
	v_mfma_f32_32x32x16_bf16 v[136:151], v[40:43], v[244:247], v[136:151]
	ds_read_b128 v[4:7], v216 offset:33632
	v_fma_f32 v152, |v120|, v82, v152
	v_fma_f32 v153, |v121|, v82, v153
	v_fma_f32 v154, |v122|, v82, v154
	v_fma_f32 v155, |v123|, v82, v155
	v_fma_f32 v156, |v124|, v82, v156
	v_fma_f32 v157, |v125|, v82, v157
	v_fma_f32 v158, |v126|, v82, v158
	v_fma_f32 v159, |v127|, v82, v159
	v_fma_f32 v160, |v128|, v82, v160
	v_fma_f32 v161, |v129|, v82, v161
	v_fma_f32 v98, |v130|, v82, v98
	v_fma_f32 v99, |v131|, v82, v99
	v_fma_f32 v100, |v132|, v82, v100
	v_fma_f32 v101, |v133|, v82, v101
	v_fma_f32 v102, |v134|, v82, v102
	v_fma_f32 v103, |v135|, v82, v103
	s_waitcnt lgkmcnt(0)
	v_mfma_f32_32x32x16_bf16 v[104:119], v[44:47], v[248:251], 0
	v_mfma_f32_32x32x16_bf16 v[104:119], v[40:43], v[4:7], v[104:119]
	ds_read_b128 v[8:11], v216 offset:33664
	ds_read_b128 v[12:15], v216 offset:33696
	v_fma_f32 v152, |v136|, v83, v152
	v_fma_f32 v153, |v137|, v83, v153
	v_fma_f32 v154, |v138|, v83, v154
	v_fma_f32 v155, |v139|, v83, v155
	v_fma_f32 v156, |v140|, v83, v156
	v_fma_f32 v157, |v141|, v83, v157
	v_fma_f32 v158, |v142|, v83, v158
	v_fma_f32 v159, |v143|, v83, v159
	v_fma_f32 v160, |v144|, v83, v160
	v_fma_f32 v161, |v145|, v83, v161
	v_fma_f32 v98, |v146|, v83, v98
	v_fma_f32 v99, |v147|, v83, v99
	v_fma_f32 v100, |v148|, v83, v100
	v_fma_f32 v101, |v149|, v83, v101
	v_fma_f32 v102, |v150|, v83, v102
	v_fma_f32 v103, |v151|, v83, v103
	s_waitcnt lgkmcnt(0)
	v_mfma_f32_32x32x16_bf16 v[120:135], v[44:47], v[8:11], 0
	v_mfma_f32_32x32x16_bf16 v[120:135], v[40:43], v[12:15], v[120:135]
	ds_read_b128 v[0:3], v216 offset:33728
	ds_read_b128 v[4:7], v216 offset:33760
	v_fma_f32 v152, |v104|, v84, v152
	v_fma_f32 v153, |v105|, v84, v153
	v_fma_f32 v154, |v106|, v84, v154
	v_fma_f32 v155, |v107|, v84, v155
	v_fma_f32 v156, |v108|, v84, v156
	v_fma_f32 v157, |v109|, v84, v157
	v_fma_f32 v158, |v110|, v84, v158
	v_fma_f32 v159, |v111|, v84, v159
	v_fma_f32 v160, |v112|, v84, v160
	v_fma_f32 v161, |v113|, v84, v161
	v_fma_f32 v98, |v114|, v84, v98
	v_fma_f32 v99, |v115|, v84, v99
	v_fma_f32 v100, |v116|, v84, v100
	v_fma_f32 v101, |v117|, v84, v101
	v_fma_f32 v102, |v118|, v84, v102
	v_fma_f32 v103, |v119|, v84, v103
	s_waitcnt lgkmcnt(0)
	v_mfma_f32_32x32x16_bf16 v[136:151], v[44:47], v[0:3], 0
	v_mfma_f32_32x32x16_bf16 v[136:151], v[40:43], v[4:7], v[136:151]
	v_fma_f32 v152, |v120|, v85, v152
	v_fma_f32 v153, |v121|, v85, v153
	v_fma_f32 v154, |v122|, v85, v154
	v_fma_f32 v155, |v123|, v85, v155
	v_fma_f32 v156, |v124|, v85, v156
	v_fma_f32 v157, |v125|, v85, v157
	v_fma_f32 v158, |v126|, v85, v158
	v_fma_f32 v159, |v127|, v85, v159
	v_fma_f32 v160, |v128|, v85, v160
	v_fma_f32 v161, |v129|, v85, v161
	v_fma_f32 v98, |v130|, v85, v98
	v_fma_f32 v99, |v131|, v85, v99
	v_fma_f32 v100, |v132|, v85, v100
	v_fma_f32 v101, |v133|, v85, v101
	v_fma_f32 v102, |v134|, v85, v102
	v_fma_f32 v103, |v135|, v85, v103
	v_fma_f32 v40, |v136|, v86, v152
	v_fma_f32 v22, |v137|, v86, v153
	v_fma_f32 v21, |v138|, v86, v154
	v_fma_f32 v20, |v139|, v86, v155
	v_fma_f32 v19, |v140|, v86, v156
	v_fma_f32 v18, |v141|, v86, v157
	v_fma_f32 v17, |v142|, v86, v158
	v_fma_f32 v16, |v143|, v86, v159
	v_fma_f32 v7, |v144|, v86, v160
	v_fma_f32 v6, |v145|, v86, v161
	v_fma_f32 v5, |v146|, v86, v98
	v_fma_f32 v4, |v147|, v86, v99
	v_fma_f32 v3, |v148|, v86, v100
	v_fma_f32 v2, |v149|, v86, v101
	v_fma_f32 v1, |v150|, v86, v102
	v_fma_f32 v0, |v151|, v86, v103
	v_ashrrev_i32_e32 v8, 31, v40
	v_bitop3_b32 v8, v8, v40, s67 bitop3:0x36
	v_lshrrev_b32_e32 v9, s58, v8
	v_lshrrev_b32_e32 v8, 8, v9
	v_cmp_eq_u32_e64 s[52:53], v8, v94
	s_and_saveexec_b64 s[64:65], s[0:1]
	s_xor_b64 s[64:65], exec, s[64:65]
	s_cbranch_execnz .LBB0_271
	s_andn2_saveexec_b64 s[64:65], s[64:65]
	s_cbranch_execnz .LBB0_302
